# combined: scalar K-address product + s_nop fills, redundant lgkmcnt waits removed in the GQA loop, dead running-max broadcast skipped in the neighbourhood loops (on top of the max/m0/DMA trims)
# speedup vs baseline: 1.0042x; 1.0042x over previous
.LBB0_707:
	s_add_i32 s22, s23, 2
	v_add_u32_e32 v186, s0, v207
	ds_read_b64_tr_b16 v[178:179], v186 offset:24576
	ds_read_b64_tr_b16 v[180:181], v186 offset:25088
	v_mfma_f32_32x32x16_bf16 v[98:113], v[174:177], v[142:145], v[34:49]
	v_add_f32_e32 v82, v66, v67
	v_add_f32_e32 v82, v68, v82
	v_add_f32_e32 v82, v69, v82
	v_add_f32_e32 v82, v70, v82
	v_add_f32_e32 v82, v71, v82
	v_cvt_pk_bf16_f32 v134, v66, v67
	v_cvt_pk_bf16_f32 v135, v68, v69
	ds_read_b64_tr_b16 v[174:175], v186 offset:28672
	ds_read_b64_tr_b16 v[176:177], v186 offset:29184
	v_add_f32_e32 v66, v72, v82
	v_mfma_f32_32x32x16_bf16 v[82:97], v[170:173], v[142:145], v[34:49]
	v_add_f32_e32 v66, v73, v66
	v_add_f32_e32 v66, v74, v66
	v_add_f32_e32 v114, v75, v66
	v_cvt_pk_bf16_f32 v136, v70, v71
	v_cvt_pk_bf16_f32 v137, v72, v73
	ds_read_b64_tr_b16 v[66:67], v186 offset:25600
	ds_read_b64_tr_b16 v[68:69], v186 offset:26112
	v_mfma_f32_32x32x16_bf16 v[98:113], v[166:169], v[138:141], v[98:113]
	v_add_f32_e32 v70, v76, v114
	v_add_f32_e32 v70, v77, v70
	v_add_f32_e32 v70, v78, v70
	v_add_f32_e32 v114, v79, v70
	v_cvt_pk_bf16_f32 v126, v74, v75
	v_cvt_pk_bf16_f32 v127, v76, v77
	ds_read_b64_tr_b16 v[70:71], v186 offset:29696
	ds_read_b64_tr_b16 v[72:73], v186 offset:30208
	v_mfma_f32_32x32x16_bf16 v[82:97], v[162:165], v[138:141], v[82:97]
	v_add_f32_e32 v74, v80, v114
	v_add_f32_e32 v74, v81, v74
	v_add_f32_e32 v74, v50, v74
	v_add_f32_e32 v114, v51, v74
	v_cvt_pk_bf16_f32 v128, v78, v79
	v_cvt_pk_bf16_f32 v129, v80, v81
	ds_read_b64_tr_b16 v[74:75], v186 offset:26624
	ds_read_b64_tr_b16 v[76:77], v186 offset:27136
	v_mfma_f32_32x32x16_bf16 v[98:113], v[158:161], v[130:133], v[98:113]
	v_add_f32_e32 v78, v52, v114
	v_add_f32_e32 v78, v53, v78
	v_add_f32_e32 v78, v54, v78
	v_add_f32_e32 v78, v55, v78
	v_cvt_pk_bf16_f32 v118, v50, v51
	v_cvt_pk_bf16_f32 v119, v52, v53
	ds_read_b64_tr_b16 v[50:51], v186 offset:30720
	ds_read_b64_tr_b16 v[52:53], v186 offset:31232
	v_mfma_f32_32x32x16_bf16 v[82:97], v[154:157], v[130:133], v[82:97]
	v_add_f32_e32 v78, v56, v78
	v_add_f32_e32 v78, v57, v78
	v_add_f32_e32 v78, v58, v78
	v_add_f32_e32 v78, v59, v78
	v_cvt_pk_bf16_f32 v120, v54, v55
	v_cvt_pk_bf16_f32 v121, v56, v57
	ds_read_b64_tr_b16 v[54:55], v186 offset:27648
	ds_read_b64_tr_b16 v[56:57], v186 offset:28160
	v_mfma_f32_32x32x16_bf16 v[98:113], v[150:153], v[122:125], v[98:113]
	v_add_f32_e32 v78, v60, v78
	v_add_f32_e32 v78, v61, v78
	v_add_f32_e32 v78, v62, v78
	v_add_f32_e32 v78, v63, v78
	v_cvt_pk_bf16_f32 v114, v58, v59
	v_cvt_pk_bf16_f32 v115, v60, v61
	ds_read_b64_tr_b16 v[58:59], v186 offset:31744
	ds_read_b64_tr_b16 v[60:61], v186 offset:32256
	v_mfma_f32_32x32x16_bf16 v[82:97], v[146:149], v[122:125], v[82:97]
	v_add_f32_e32 v78, v64, v78
	v_add_f32_e32 v78, v65, v78
	v_cvt_pk_bf16_f32 v116, v62, v63
	v_cvt_pk_bf16_f32 v117, v64, v65
	s_cmpk_gt_u32 s22, 0x7c
	s_cselect_b64 s[0:1], -1, 0
	s_cmpk_lt_u32 s22, 0x7d
	s_cselect_b32 s4, 0, 0xffffff80
	s_cselect_b32 s5, s9, s20
	s_add_i32 s4, s4, s23
	s_lshl_b32 s4, s4, 6
	s_add_i32 s4, s4, s5
	s_addk_i32 s4, 0x140
	s_mul_i32 s4, s4, 0xe00
	s_mov_b32 s5, 0
	s_add_i32 m0, s24, s18
	v_lshl_add_u64 v[62:63], v[192:193], 0, s[4:5]
	global_load_lds_dwordx4 v[62:63], off
	v_max_f32_e32 v62, v98, v99
	v_max3_f32 v63, v100, v101, v83
	v_max3_f32 v62, v62, v82, v84
	v_max3_f32 v62, v62, v85, v102
	v_max3_f32 v63, v63, v104, v105
	v_max3_f32 v62, v62, v103, v86
	v_max3_f32 v63, v63, v88, v89
	v_max3_f32 v62, v62, v87, v106
	v_max3_f32 v63, v63, v108, v109
	v_max3_f32 v62, v62, v107, v90
	v_max3_f32 v63, v63, v92, v93
	v_max3_f32 v62, v62, v91, v110
	v_max3_f32 v63, v63, v112, v113
	v_max3_f32 v62, v62, v111, v94
	v_max3_f32 v63, v63, v96, v97
	v_max3_f32 v62, v62, v95, v63
	v_mov_b32_e32 v63, v62
	s_add_i32 m0, s21, s19
	v_add_f32_e32 v224, v224, v78
	v_permlane32_swap_b32_e32 v62, v63
	global_load_lds_dwordx4 v[196:197], off
	v_max_f32_e32 v62, v62, v63
	v_cmp_lt_f32_e32 vcc, s51, v62
	s_cmp_lg_u64 vcc, 0
	s_cselect_b64 s[4:5], -1, 0
	s_cbranch_vccnz .LBB0_715

.LBB0_710:
	s_add_i32 s4, s21, 0x2000
	s_cmpk_lg_i32 s21, 0x4000
	s_cselect_b32 s25, s4, 0
	v_add_u32_e32 v186, s24, v207
	ds_read_b64_tr_b16 v[150:151], v186 offset:24576
	ds_read_b64_tr_b16 v[152:153], v186 offset:25088
	v_mfma_f32_32x32x16_bf16 v[66:81], v[62:65], v[142:145], v[34:49]
	v_add_f32_e32 v50, v98, v99
	v_add_f32_e32 v50, v100, v50
	v_add_f32_e32 v50, v101, v50
	v_add_f32_e32 v50, v102, v50
	v_add_f32_e32 v50, v103, v50
	v_cvt_pk_bf16_f32 v134, v98, v99
	v_cvt_pk_bf16_f32 v135, v100, v101
	ds_read_b64_tr_b16 v[146:147], v186 offset:28672
	ds_read_b64_tr_b16 v[148:149], v186 offset:29184
	v_add_f32_e32 v50, v104, v50
	v_add_f32_e32 v50, v105, v50
	v_add_f32_e32 v50, v106, v50
	v_add_f32_e32 v114, v107, v50
	v_mfma_f32_32x32x16_bf16 v[50:65], v[174:177], v[142:145], v[34:49]
	v_cvt_pk_bf16_f32 v136, v102, v103
	v_cvt_pk_bf16_f32 v137, v104, v105
	ds_read_b64_tr_b16 v[98:99], v186 offset:25600
	ds_read_b64_tr_b16 v[100:101], v186 offset:26112
	v_mfma_f32_32x32x16_bf16 v[66:81], v[178:181], v[138:141], v[66:81]
	v_add_f32_e32 v102, v108, v114
	v_add_f32_e32 v102, v109, v102
	v_add_f32_e32 v102, v110, v102
	v_add_f32_e32 v114, v111, v102
	v_cvt_pk_bf16_f32 v126, v106, v107
	v_cvt_pk_bf16_f32 v127, v108, v109
	ds_read_b64_tr_b16 v[102:103], v186 offset:29696
	ds_read_b64_tr_b16 v[104:105], v186 offset:30208
	v_mfma_f32_32x32x16_bf16 v[50:65], v[170:173], v[138:141], v[50:65]
	v_add_f32_e32 v106, v112, v114
	v_add_f32_e32 v106, v113, v106
	v_add_f32_e32 v106, v82, v106
	v_add_f32_e32 v114, v83, v106
	v_cvt_pk_bf16_f32 v128, v110, v111
	v_cvt_pk_bf16_f32 v129, v112, v113
	ds_read_b64_tr_b16 v[106:107], v186 offset:26624
	ds_read_b64_tr_b16 v[108:109], v186 offset:27136
	v_mfma_f32_32x32x16_bf16 v[66:81], v[166:169], v[130:133], v[66:81]
	v_add_f32_e32 v110, v84, v114
	v_add_f32_e32 v110, v85, v110
	v_add_f32_e32 v110, v86, v110
	v_add_f32_e32 v110, v87, v110
	v_cvt_pk_bf16_f32 v118, v82, v83
	v_cvt_pk_bf16_f32 v119, v84, v85
	ds_read_b64_tr_b16 v[82:83], v186 offset:30720
	ds_read_b64_tr_b16 v[84:85], v186 offset:31232
	v_mfma_f32_32x32x16_bf16 v[50:65], v[162:165], v[130:133], v[50:65]
	v_add_f32_e32 v110, v88, v110
	v_add_f32_e32 v110, v89, v110
	v_add_f32_e32 v110, v90, v110
	v_add_f32_e32 v110, v91, v110
	v_cvt_pk_bf16_f32 v120, v86, v87
	v_cvt_pk_bf16_f32 v121, v88, v89
	ds_read_b64_tr_b16 v[86:87], v186 offset:27648
	ds_read_b64_tr_b16 v[88:89], v186 offset:28160
	v_mfma_f32_32x32x16_bf16 v[66:81], v[158:161], v[122:125], v[66:81]
	v_add_f32_e32 v110, v92, v110
	v_add_f32_e32 v110, v93, v110
	v_add_f32_e32 v110, v94, v110
	v_add_f32_e32 v110, v95, v110
	v_cvt_pk_bf16_f32 v114, v90, v91
	v_cvt_pk_bf16_f32 v115, v92, v93
	ds_read_b64_tr_b16 v[90:91], v186 offset:31744
	ds_read_b64_tr_b16 v[92:93], v186 offset:32256
	v_mfma_f32_32x32x16_bf16 v[50:65], v[154:157], v[122:125], v[50:65]
	v_add_f32_e32 v110, v96, v110
	v_add_f32_e32 v110, v97, v110
	v_cvt_pk_bf16_f32 v116, v94, v95
	v_cvt_pk_bf16_f32 v117, v96, v97
	s_cmpk_lt_u32 s22, 0x7c
	s_cselect_b32 s4, 0, 0xffffff80
	s_cselect_b32 s5, s9, s20
	s_add_i32 s4, s4, s23
	s_lshl_b32 s4, s4, 6
	s_add_i32 s4, s4, s5
	s_addk_i32 s4, 0x180
	s_mul_i32 s4, s4, 0xe00
	s_mov_b32 s5, 0
	s_add_i32 m0, s21, s18
	v_lshl_add_u64 v[94:95], v[192:193], 0, s[4:5]
	global_load_lds_dwordx4 v[94:95], off
	s_add_i32 m0, s25, s19
	v_lshl_add_u64 v[94:95], v[196:197], 0, s[30:31]
	global_load_lds_dwordx4 v[94:95], off
	v_max_f32_e32 v94, v66, v67
	v_max3_f32 v95, v68, v69, v51
	v_max3_f32 v94, v94, v50, v52
	v_max3_f32 v94, v94, v53, v70
	v_max3_f32 v95, v95, v72, v73
	v_max3_f32 v94, v94, v71, v54
	v_max3_f32 v95, v95, v56, v57
	v_max3_f32 v94, v94, v55, v74
	v_max3_f32 v95, v95, v76, v77
	v_max3_f32 v94, v94, v75, v58
	v_max3_f32 v95, v95, v60, v61
	v_max3_f32 v94, v94, v59, v78
	v_max3_f32 v95, v95, v80, v81
	v_max3_f32 v94, v94, v79, v62
	v_max3_f32 v95, v95, v64, v65
	v_max3_f32 v94, v94, v63, v95
	v_mov_b32_e32 v95, v94
	v_add_f32_e32 v224, v224, v110
	s_nop 0
	v_permlane32_swap_b32_e32 v94, v95
	v_max_f32_e32 v94, v94, v95
	v_cmp_lt_f32_e32 vcc, s51, v94
	s_cmp_lg_u64 vcc, 0
	s_cselect_b64 s[4:5], -1, 0
	s_cbranch_vccnz .LBB0_718
